# v33 + non-temporal hint on the final phase's read-once residual row loads
# speedup vs baseline: 1.0076x; 1.0054x over previous
.LBB0_912:
	s_and_b64 vcc, exec, s[4:5]
	s_cbranch_vccz .LBB0_1039
	s_waitcnt vmcnt(0)
	v_ashrrev_i32_e32 v28, 6, v186
	s_lshl_b32 s6, s64, 3
	v_add_u32_e32 v46, s6, v28
	v_cmp_gt_i32_e32 vcc, s70, v46
	s_waitcnt lgkmcnt(0)
	s_and_saveexec_b64 s[12:13], vcc
	s_cbranch_execz .LBB0_922
	s_load_dwordx4 s[8:11], s[80:81], 0xe8
	v_and_b32_e32 v20, 63, v186
	v_lshlrev_b32_e32 v34, 4, v20
	v_lshlrev_b32_e32 v180, 3, v20
	v_lshl_add_u32 v20, s75, 3, v46
	v_min_i32_e32 v20, 0x7fff, v20
	v_ashrrev_i32_e32 v21, 31, v20
	v_lshlrev_b64 v[20:21], 12, v[20:21]
	s_waitcnt lgkmcnt(0)
	v_lshl_add_u64 v[20:21], s[10:11], 0, v[20:21]
	v_lshl_add_u64 v[20:21], v[20:21], 0, v[180:181]
	v_ashrrev_i32_e32 v47, 31, v46
	global_load_dwordx4 v[4:7], v34, s[8:9]
	global_load_dwordx4 v[8:11], v34, s[8:9] offset:1024
	global_load_dwordx4 v[12:15], v34, s[8:9] offset:2048
	global_load_dwordx4 v[16:19], v34, s[8:9] offset:3072
	global_load_dwordx2 v[44:45], v[20:21], off nt
	global_load_dwordx2 v[42:43], v[20:21], off offset:512 nt
	global_load_dwordx2 v[32:33], v[20:21], off offset:1024 nt
	global_load_dwordx2 v[30:31], v[20:21], off offset:1536 nt
	v_lshlrev_b64 v[20:21], 12, v[46:47]
	v_lshl_add_u64 v[20:21], s[10:11], 0, v[20:21]
	v_lshl_add_u64 v[20:21], v[20:21], 0, v[180:181]
	global_load_dwordx2 v[54:55], v[20:21], off nt
	global_load_dwordx2 v[52:53], v[20:21], off offset:512 nt
	global_load_dwordx2 v[50:51], v[20:21], off offset:1024 nt
	global_load_dwordx2 v[48:49], v[20:21], off offset:1536 nt
	s_lshl_b32 s8, s75, 4
	s_add_i32 s0, s6, s8
	v_add_u32_e32 v24, s0, v28
	v_ashrrev_i32_e32 v29, 31, v28
	s_ashr_i32 s7, s6, 31
	v_ashrrev_i32_e32 v25, 31, v24
	v_lshl_add_u64 v[26:27], v[28:29], 0, s[6:7]
	v_lshl_add_u64 v[20:21], s[10:11], 0, v[180:181]
	v_lshlrev_b64 v[24:25], 12, v[24:25]
	s_ashr_i32 s9, s8, 31
	v_lshlrev_b64 v[26:27], 12, v[26:27]
	s_add_i32 s0, s64, s75
	v_lshl_add_u64 v[22:23], v[20:21], 0, v[180:181]
	v_or_b32_e32 v24, v24, v180
	s_lshl_b64 s[14:15], s[8:9], 12
	v_or_b32_e32 v26, v26, v34
	v_lshl_add_u32 v28, s0, 3, v28
	s_mov_b64 s[16:17], 0
	s_branch .LBB0_917

.LBB0_917:
	v_add_u32_e32 v56, s8, v46
	s_movk_i32 s0, 0x7fff
	v_cmp_gt_i32_e64 s[6:7], s70, v56
	v_cmp_lt_i32_e32 vcc, s0, v56
	s_waitcnt vmcnt(3)
	v_mov_b32_e32 v34, v54
	v_mov_b32_e32 v35, v55
	s_waitcnt vmcnt(2)
	v_mov_b32_e32 v36, v52
	v_mov_b32_e32 v37, v53
	s_waitcnt vmcnt(1)
	v_mov_b32_e32 v38, v50
	v_mov_b32_e32 v39, v51
	s_waitcnt vmcnt(0)
	v_mov_b32_e32 v40, v48
	v_mov_b32_e32 v41, v49
	s_and_saveexec_b64 s[4:5], s[6:7]
	s_cbranch_execz .LBB0_919
	v_lshl_add_u64 v[40:41], s[10:11], 0, v[24:25]
	global_load_dwordx2 v[34:35], v[40:41], off nt
	global_load_dwordx2 v[36:37], v[40:41], off offset:512 nt
	global_load_dwordx2 v[38:39], v[40:41], off offset:1024 nt
	s_nop 0
	global_load_dwordx2 v[40:41], v[40:41], off offset:1536 nt
.LBB0_919:
	s_or_b64 exec, exec, s[4:5]
	v_lshlrev_b32_e32 v59, 16, v55
	v_lshlrev_b32_e32 v58, 16, v54
	v_and_b32_e32 v55, 0xffff0000, v55
	v_and_b32_e32 v54, 0xffff0000, v54
	v_lshlrev_b32_e32 v66, 16, v48
	v_and_b32_e32 v29, 0xffff0000, v48
	v_lshlrev_b32_e32 v68, 16, v49
	v_and_b32_e32 v69, 0xffff0000, v49
	v_pk_mul_f32 v[48:49], v[54:55], v[54:55]
	v_lshlrev_b32_e32 v61, 16, v53
	v_lshlrev_b32_e32 v60, 16, v52
	v_and_b32_e32 v53, 0xffff0000, v53
	v_and_b32_e32 v52, 0xffff0000, v52
	v_pk_fma_f32 v[48:49], v[58:59], v[58:59], v[48:49]
	v_lshlrev_b32_e32 v62, 16, v50
	v_and_b32_e32 v63, 0xffff0000, v50
	v_lshlrev_b32_e32 v64, 16, v51
	v_and_b32_e32 v65, 0xffff0000, v51
	v_pk_add_f32 v[48:49], v[48:49], v[48:49] op_sel_hi:[0,1]
	v_pk_mul_f32 v[50:51], v[52:53], v[52:53]
	v_mul_f32_e32 v67, v62, v62
	v_pk_fma_f32 v[50:51], v[60:61], v[60:61], v[50:51]
	v_mul_f32_e32 v71, v63, v63
	v_mul_f32_e32 v48, v64, v64
	v_mov_b32_e32 v70, v66
	v_pk_add_f32 v[50:51], v[50:51], v[50:51] op_sel_hi:[0,1]
	v_pk_fma_f32 v[72:73], v[64:65], v[64:65], v[48:49] op_sel_hi:[1,1,0]
	v_pk_add_f32 v[70:71], v[66:67], v[70:71]
	v_mul_f32_e32 v72, v29, v29
	v_mul_f32_e32 v48, v68, v68
	v_mul_f32_e32 v50, v69, v69
	v_mul_f32_e32 v74, v66, v66
	v_mov_b32_e32 v75, v71
	v_pk_add_f32 v[70:71], v[74:75], v[72:73]
	v_pk_add_f32 v[48:49], v[48:49], v[50:51]
	v_mov_b32_e32 v67, v29
	v_pk_add_f32 v[48:49], v[70:71], v[48:49]
	v_cmp_gt_i32_e64 s[6:7], s70, v28
	v_add_f32_e32 v47, v48, v49
	v_mov_b32_e32 v48, v181
	v_mov_b32_e32 v49, v54
	v_add_f32_dpp v47, v47, v47 row_shr:1 row_mask:0xf bank_mask:0xf bound_ctrl:1
	v_mov_b32_e32 v54, v59
	s_nop 0
	v_add_f32_dpp v47, v47, v47 row_shr:2 row_mask:0xf bank_mask:0xf bound_ctrl:1
	s_nop 1
	v_add_f32_dpp v47, v47, v47 row_shr:4 row_mask:0xf bank_mask:0xf bound_ctrl:1
	s_nop 1
	v_add_f32_dpp v47, v47, v47 row_shr:8 row_mask:0xf bank_mask:0xf bound_ctrl:1
	s_nop 1
	v_mov_b32_dpp v48, v47 row_bcast:15 row_mask:0xa bank_mask:0xf
	v_add_f32_e32 v47, v47, v48
	v_mov_b32_e32 v48, v181
	s_nop 1
	v_mov_b32_dpp v48, v47 row_bcast:31 row_mask:0xc bank_mask:0xf
	v_add_f32_e32 v47, v47, v48
	v_mov_b32_e32 v48, v58
	v_readlane_b32 s0, v47, 63
	s_nop 1
	v_fma_f32 v47, s0, v247, v237
	v_rsq_f32_e32 v70, v47
	s_nop 0
	v_pk_mul_f32 v[48:49], v[70:71], v[48:49] op_sel_hi:[0,1]
	v_pk_mul_f32 v[50:51], v[70:71], v[54:55] op_sel_hi:[0,1]
	v_pk_mul_f32 v[50:51], v[6:7], v[50:51]
	v_pk_mul_f32 v[48:49], v[4:5], v[48:49]
	v_lshl_add_u64 v[54:55], s[10:11], 0, v[26:27]
	global_store_dwordx4 v[54:55], v[48:51], off nt
	s_nop 1
	v_mov_b32_e32 v48, v60
	v_mov_b32_e32 v49, v52
	v_mov_b32_e32 v52, v61
	v_pk_mul_f32 v[48:49], v[70:71], v[48:49] op_sel_hi:[0,1]
	v_pk_mul_f32 v[50:51], v[70:71], v[52:53] op_sel_hi:[0,1]
	v_pk_mul_f32 v[50:51], v[10:11], v[50:51]
	v_pk_mul_f32 v[48:49], v[8:9], v[48:49]
	global_store_dwordx4 v[54:55], v[48:51], off offset:1024 nt
	s_nop 1
	v_pk_mul_f32 v[48:49], v[70:71], v[62:63] op_sel_hi:[0,1]
	v_pk_mul_f32 v[50:51], v[70:71], v[64:65] op_sel_hi:[0,1]
	v_pk_mul_f32 v[50:51], v[14:15], v[50:51]
	v_pk_mul_f32 v[48:49], v[12:13], v[48:49]
	global_store_dwordx4 v[54:55], v[48:51], off offset:2048 nt
	s_nop 1
	v_pk_mul_f32 v[48:49], v[70:71], v[66:67] op_sel_hi:[0,1]
	v_pk_mul_f32 v[50:51], v[70:71], v[68:69] op_sel_hi:[0,1]
	v_pk_mul_f32 v[50:51], v[18:19], v[50:51]
	v_pk_mul_f32 v[48:49], v[16:17], v[48:49]
	global_store_dwordx4 v[54:55], v[48:51], off offset:3072 nt
	s_and_saveexec_b64 s[18:19], s[6:7]
	s_cbranch_execz .LBB0_916
	s_mul_i32 s0, s75, 24
	v_add_u32_e32 v54, s0, v46
	v_cmp_gt_i32_e64 s[6:7], s70, v54
	v_mov_b32_e32 v46, v44
	v_mov_b32_e32 v47, v45
	v_mov_b32_e32 v48, v42
	v_mov_b32_e32 v49, v43
	v_mov_b32_e32 v50, v32
	v_mov_b32_e32 v51, v33
	v_mov_b32_e32 v52, v30
	v_mov_b32_e32 v53, v31
	s_and_saveexec_b64 s[20:21], s[6:7]
	s_cbranch_execz .LBB0_915
	v_ashrrev_i32_e32 v55, 31, v54
	v_lshlrev_b64 v[46:47], 12, v[54:55]
	v_lshl_add_u64 v[52:53], v[20:21], 0, v[46:47]
	global_load_dwordx2 v[46:47], v[52:53], off nt
	global_load_dwordx2 v[48:49], v[52:53], off offset:512 nt
	global_load_dwordx2 v[50:51], v[52:53], off offset:1024 nt
	s_nop 0
	global_load_dwordx2 v[52:53], v[52:53], off offset:1536 nt
	s_branch .LBB0_915
